# prompt attention: z gate loads also as four 16-byte loads per head with half-wave exchange
# speedup vs baseline: 1.0118x; 1.0007x over previous
.LBB0_2056:
	v_mov_b32_e32 v96, v101
	ds_read_b128 v[0:3], v135
	ds_read_b128 v[4:7], v135 offset:32
	s_load_dwordx2 s[0:1], s[40:41], 0x80
	s_add_i32 s39, s45, s38
	s_waitcnt lgkmcnt(0)
	v_mfma_f32_32x32x16_bf16 v[64:79], v[0:3], v[80:83], 0
	ds_read_b128 v[0:3], v135 offset:64
	s_add_u32 s0, s0, s36
	s_addc_u32 s1, s1, s37
	s_add_i32 s38, s38, 1
	s_nop 0
	v_mfma_f32_32x32x16_bf16 v[64:79], v[4:7], v[84:87], v[64:79]
	s_waitcnt lgkmcnt(0)
	v_mfma_f32_32x32x16_bf16 v[64:79], v[0:3], v[88:91], v[64:79]
	ds_read_b128 v[0:3], v135 offset:96
	s_waitcnt lgkmcnt(0)
	v_mfma_f32_32x32x16_bf16 v[64:79], v[0:3], v[92:95], v[64:79]
	ds_read_b128 v[0:3], v135 offset:4608
	s_waitcnt lgkmcnt(0)
	v_mfma_f32_32x32x16_bf16 v[48:63], v[0:3], v[80:83], 0
	ds_read_b128 v[0:3], v135 offset:4640
	s_waitcnt lgkmcnt(0)
	v_mfma_f32_32x32x16_bf16 v[48:63], v[0:3], v[84:87], v[48:63]
	ds_read_b128 v[0:3], v135 offset:4672
	s_waitcnt lgkmcnt(0)
	v_mfma_f32_32x32x16_bf16 v[48:63], v[0:3], v[88:91], v[48:63]
	ds_read_b128 v[0:3], v135 offset:4704
	s_waitcnt lgkmcnt(0)
	v_mfma_f32_32x32x16_bf16 v[48:63], v[0:3], v[92:95], v[48:63]
	ds_read_b128 v[0:3], v135 offset:9216
	s_waitcnt lgkmcnt(0)
	v_mfma_f32_32x32x16_bf16 v[32:47], v[0:3], v[80:83], 0
	ds_read_b128 v[0:3], v135 offset:9248
	s_waitcnt lgkmcnt(0)
	v_mfma_f32_32x32x16_bf16 v[32:47], v[0:3], v[84:87], v[32:47]
	ds_read_b128 v[0:3], v135 offset:9280
	s_waitcnt lgkmcnt(0)
	v_mfma_f32_32x32x16_bf16 v[32:47], v[0:3], v[88:91], v[32:47]
	ds_read_b128 v[0:3], v135 offset:9312
	s_waitcnt lgkmcnt(0)
	v_mfma_f32_32x32x16_bf16 v[32:47], v[0:3], v[92:95], v[32:47]
	ds_read_b128 v[0:3], v135 offset:13824
	s_waitcnt lgkmcnt(0)
	v_mfma_f32_32x32x16_bf16 v[16:31], v[0:3], v[80:83], 0
	ds_read_b128 v[0:3], v135 offset:13856
	s_waitcnt lgkmcnt(0)
	v_mfma_f32_32x32x16_bf16 v[16:31], v[0:3], v[84:87], v[16:31]
	ds_read_b128 v[0:3], v135 offset:13888
	s_waitcnt lgkmcnt(0)
	v_mfma_f32_32x32x16_bf16 v[16:31], v[0:3], v[88:91], v[16:31]
	ds_read_b128 v[0:3], v135 offset:13920
	s_waitcnt lgkmcnt(0)
	v_mfma_f32_32x32x16_bf16 v[16:31], v[0:3], v[92:95], v[16:31]
	ds_read_b128 v[0:3], v135 offset:18432
	s_waitcnt lgkmcnt(0)
	v_mfma_f32_32x32x16_bf16 v[0:15], v[0:3], v[80:83], 0
	ds_read_b128 v[80:83], v135 offset:18464
	s_waitcnt lgkmcnt(0)
	v_mfma_f32_32x32x16_bf16 v[0:15], v[80:83], v[84:87], v[0:15]
	ds_read_b128 v[80:83], v135 offset:18496
	s_waitcnt lgkmcnt(0)
	v_mfma_f32_32x32x16_bf16 v[0:15], v[80:83], v[88:91], v[0:15]
	ds_read_b128 v[80:83], v135 offset:18528
	s_waitcnt lgkmcnt(0)
	v_mfma_f32_32x32x16_bf16 v[0:15], v[80:83], v[92:95], v[0:15]
	global_load_dword v80, v97, s[0:1]
	v_add_u32_e32 v94, 0x80, v96
	v_cmp_le_i32_e64 s[0:1], v100, v96
	v_cmp_gt_i32_e32 vcc, v100, v94
	s_or_b64 s[0:1], s[0:1], vcc
	v_readlane_b32 vcc_lo, v254, 37
	v_readlane_b32 vcc_hi, v254, 38
	s_or_b64 vcc, s[0:1], vcc
	v_cmp_ge_i32_e64 s[0:1], v100, v94
	v_cndmask_b32_e32 v64, v64, v200, vcc
	v_cmp_lt_i32_e32 vcc, v100, v96
	s_or_b64 s[0:1], vcc, s[0:1]
	v_readlane_b32 vcc_lo, v254, 39
	v_readlane_b32 vcc_hi, v254, 40
	s_or_b64 vcc, s[0:1], vcc
	v_cmp_gt_i32_e64 s[0:1], v104, v94
	v_cndmask_b32_e32 v65, v65, v200, vcc
	v_cmp_le_i32_e32 vcc, v104, v96
	s_or_b64 s[0:1], vcc, s[0:1]
	v_readlane_b32 vcc_lo, v254, 20
	v_readlane_b32 vcc_hi, v254, 21
	s_or_b64 vcc, s[0:1], vcc
	v_cmp_gt_i32_e64 s[0:1], v105, v94
	v_cndmask_b32_e32 v66, v66, v200, vcc
	v_cmp_le_i32_e32 vcc, v105, v96
	s_or_b64 s[0:1], vcc, s[0:1]
	v_readlane_b32 vcc_lo, v254, 18
	v_readlane_b32 vcc_hi, v254, 19
	s_or_b64 vcc, s[0:1], vcc
	v_cmp_gt_i32_e64 s[0:1], v106, v94
	v_cndmask_b32_e32 v67, v67, v200, vcc
	v_cmp_le_i32_e32 vcc, v106, v96
	s_or_b64 s[0:1], vcc, s[0:1]
	v_readlane_b32 vcc_lo, v254, 41
	v_readlane_b32 vcc_hi, v254, 42
	s_or_b64 vcc, s[0:1], vcc
	v_cmp_gt_i32_e64 s[0:1], v107, v94
	v_cndmask_b32_e32 v68, v68, v200, vcc
	v_cmp_le_i32_e32 vcc, v107, v96
	s_or_b64 s[0:1], vcc, s[0:1]
	v_readlane_b32 vcc_lo, v254, 22
	v_readlane_b32 vcc_hi, v254, 23
	s_or_b64 vcc, s[0:1], vcc
	v_cmp_gt_i32_e64 s[0:1], v108, v94
	v_cndmask_b32_e32 v69, v69, v200, vcc
	v_cmp_le_i32_e32 vcc, v108, v96
	s_or_b64 s[0:1], vcc, s[0:1]
	v_readlane_b32 vcc_lo, v254, 24
	v_readlane_b32 vcc_hi, v254, 25
	s_or_b64 vcc, s[0:1], vcc
	v_cmp_gt_i32_e64 s[0:1], v109, v94
	v_cndmask_b32_e32 v70, v70, v200, vcc
	v_cmp_le_i32_e32 vcc, v109, v96
	s_or_b64 s[0:1], vcc, s[0:1]
	v_readlane_b32 vcc_lo, v254, 26
	v_readlane_b32 vcc_hi, v254, 27
	s_or_b64 vcc, s[0:1], vcc
	v_cmp_gt_i32_e64 s[0:1], v110, v94
	v_cndmask_b32_e32 v71, v71, v200, vcc
	v_cmp_le_i32_e32 vcc, v110, v96
	s_or_b64 s[0:1], vcc, s[0:1]
	v_readlane_b32 vcc_lo, v254, 28
	v_readlane_b32 vcc_hi, v254, 29
	s_or_b64 vcc, s[0:1], vcc
	v_cmp_gt_i32_e64 s[0:1], v111, v94
	v_cndmask_b32_e32 v72, v72, v200, vcc
	v_cmp_le_i32_e32 vcc, v111, v96
	s_or_b64 s[0:1], vcc, s[0:1]
	v_readlane_b32 vcc_lo, v254, 32
	v_readlane_b32 vcc_hi, v254, 33
	s_or_b64 vcc, s[0:1], vcc
	v_cmp_gt_i32_e64 s[0:1], v112, v94
	v_cndmask_b32_e32 v73, v73, v200, vcc
	v_cmp_le_i32_e32 vcc, v112, v96
	s_or_b64 s[0:1], vcc, s[0:1]
	v_readlane_b32 vcc_lo, v254, 34
	v_readlane_b32 vcc_hi, v254, 35
	s_or_b64 vcc, s[0:1], vcc
	v_cmp_gt_i32_e64 s[0:1], v113, v94
	v_cndmask_b32_e32 v74, v74, v200, vcc
	v_cmp_le_i32_e32 vcc, v113, v96
	s_or_b64 s[0:1], vcc, s[0:1]
	v_readlane_b32 vcc_lo, v254, 5
	v_readlane_b32 vcc_hi, v254, 6
	s_or_b64 vcc, s[0:1], vcc
	v_cmp_gt_i32_e64 s[0:1], v114, v94
	v_cndmask_b32_e32 v75, v75, v200, vcc
	v_cmp_le_i32_e32 vcc, v114, v96
	s_or_b64 s[0:1], vcc, s[0:1]
	v_readlane_b32 vcc_lo, v254, 8
	v_readlane_b32 vcc_hi, v254, 9
	s_or_b64 vcc, s[0:1], vcc
	v_cmp_gt_i32_e64 s[0:1], v115, v94
	v_cndmask_b32_e32 v76, v76, v200, vcc
	v_cmp_le_i32_e32 vcc, v115, v96
	s_or_b64 s[0:1], vcc, s[0:1]
	v_readlane_b32 vcc_lo, v254, 30
	v_readlane_b32 vcc_hi, v254, 31
	s_or_b64 vcc, s[0:1], vcc
	v_cmp_gt_i32_e64 s[0:1], v116, v94
	v_cndmask_b32_e32 v77, v77, v200, vcc
	v_cmp_le_i32_e32 vcc, v116, v96
	s_or_b64 s[0:1], vcc, s[0:1]
	v_readlane_b32 vcc_lo, v254, 58
	v_readlane_b32 vcc_hi, v254, 59
	s_or_b64 vcc, s[0:1], vcc
	v_cmp_gt_i32_e64 s[0:1], v117, v94
	v_cndmask_b32_e32 v85, v78, v200, vcc
	v_cmp_le_i32_e32 vcc, v117, v96
	s_or_b64 s[0:1], vcc, s[0:1]
	v_readlane_b32 vcc_lo, v254, 60
	v_readlane_b32 vcc_hi, v254, 61
	s_or_b64 vcc, s[0:1], vcc
	v_readlane_b32 s0, v254, 62
	v_readlane_b32 s1, v254, 63
	s_waitcnt vmcnt(0)
	v_max3_f32 v81, v80, v64, v65
	v_max3_f32 v81, v81, v66, v67
	v_cndmask_b32_e64 v93, v48, v200, s[0:1]
	v_readlane_b32 s0, v255, 0
	v_readlane_b32 s1, v255, 1
	v_max3_f32 v81, v81, v68, v69
	v_max3_f32 v81, v81, v70, v71
	v_cndmask_b32_e64 v90, v49, v200, s[0:1]
	v_readlane_b32 s0, v255, 2
	v_readlane_b32 s1, v255, 3
	v_max3_f32 v81, v81, v72, v73
	v_max3_f32 v81, v81, v74, v75
	v_cndmask_b32_e64 v91, v50, v200, s[0:1]
	v_readlane_b32 s0, v255, 4
	v_readlane_b32 s1, v255, 5
	v_max3_f32 v81, v81, v76, v77
	v_cndmask_b32_e32 v92, v79, v200, vcc
	v_cndmask_b32_e64 v88, v51, v200, s[0:1]
	v_readlane_b32 s0, v255, 6
	v_readlane_b32 s1, v255, 7
	v_max3_f32 v78, v81, v85, v92
	v_max3_f32 v48, v78, v93, v90
	v_cndmask_b32_e64 v89, v52, v200, s[0:1]
	v_readlane_b32 s0, v255, 8
	v_readlane_b32 s1, v255, 9
	v_cmp_le_i32_e32 vcc, v118, v96
	v_max3_f32 v48, v48, v91, v88
	v_cndmask_b32_e64 v86, v53, v200, s[0:1]
	v_readlane_b32 s0, v255, 10
	v_readlane_b32 s1, v255, 11
	v_max3_f32 v48, v48, v89, v86
	v_cndmask_b32_e64 v52, v39, v200, s[6:7]
	v_cndmask_b32_e64 v87, v54, v200, s[0:1]
	v_readlane_b32 s0, v255, 12
	v_readlane_b32 s1, v255, 13
	v_cndmask_b32_e64 v51, v40, v200, s[50:51]
	v_cndmask_b32_e64 v50, v41, v200, s[52:53]
	v_cndmask_b32_e64 v83, v55, v200, s[0:1]
	v_readlane_b32 s0, v255, 14
	v_readlane_b32 s1, v255, 15
	v_max3_f32 v48, v48, v87, v83
	v_cndmask_b32_e64 v49, v42, v200, s[54:55]
	v_cndmask_b32_e64 v84, v56, v200, s[0:1]
	v_readlane_b32 s0, v255, 16
	v_readlane_b32 s1, v255, 17
	v_cndmask_b32_e64 v42, v45, v200, s[60:61]
	v_cndmask_b32_e64 v41, v46, v200, s[62:63]
	v_cndmask_b32_e64 v81, v57, v200, s[0:1]
	v_readlane_b32 s0, v255, 18
	v_readlane_b32 s1, v255, 19
	v_max3_f32 v48, v48, v84, v81
	v_cndmask_b32_e64 v40, v47, v200, s[64:65]
	v_cndmask_b32_e64 v82, v58, v200, s[0:1]
	v_readlane_b32 s0, v255, 20
	v_readlane_b32 s1, v255, 21
	v_cndmask_b32_e64 v39, v16, v200, s[66:67]
	s_nop 0
	v_cndmask_b32_e64 v78, v59, v200, s[0:1]
	v_readlane_b32 s0, v255, 22
	v_readlane_b32 s1, v255, 23
	v_max3_f32 v48, v48, v82, v78
	s_nop 0
	v_cndmask_b32_e64 v79, v60, v200, s[0:1]
	v_readlane_b32 s0, v255, 24
	v_readlane_b32 s1, v255, 25
	s_nop 1
	v_cndmask_b32_e64 v61, v61, v200, s[0:1]
	v_readlane_b32 s0, v255, 26
	v_readlane_b32 s1, v255, 27
	v_max3_f32 v48, v48, v79, v61
	s_nop 0
	v_cndmask_b32_e64 v62, v62, v200, s[0:1]
	v_readlane_b32 s0, v255, 28
	v_readlane_b32 s1, v255, 29
	s_nop 1
	v_cndmask_b32_e64 v59, v63, v200, s[0:1]
	v_readlane_b32 s0, v255, 30
	v_readlane_b32 s1, v255, 31
	v_max3_f32 v48, v48, v62, v59
	s_nop 0
	v_cndmask_b32_e64 v60, v32, v200, s[0:1]
	v_readlane_b32 s0, v255, 32
	v_readlane_b32 s1, v255, 33
	s_nop 1
	v_cndmask_b32_e64 v57, v33, v200, s[0:1]
	v_readlane_b32 s0, v255, 34
	v_readlane_b32 s1, v255, 35
	v_max3_f32 v32, v48, v60, v57
	v_cndmask_b32_e64 v48, v43, v200, s[56:57]
	v_cndmask_b32_e64 v58, v34, v200, s[0:1]
	v_readlane_b32 s0, v255, 36
	v_readlane_b32 s1, v255, 37
	v_cndmask_b32_e64 v43, v44, v200, s[58:59]
	v_cndmask_b32_e64 v34, v21, v200, s[76:77]
	v_cndmask_b32_e64 v55, v35, v200, s[0:1]
	v_readlane_b32 s0, v255, 38
	v_readlane_b32 s1, v255, 39
	v_max3_f32 v32, v32, v58, v55
	v_cndmask_b32_e64 v35, v20, v200, s[74:75]
	v_cndmask_b32_e64 v56, v36, v200, s[0:1]
	v_readlane_b32 s0, v255, 40
	v_readlane_b32 s1, v255, 41
	v_cndmask_b32_e64 v36, v19, v200, s[72:73]
	v_cndmask_b32_e64 v33, v22, v200, s[78:79]
	v_cndmask_b32_e64 v53, v37, v200, s[0:1]
	v_readlane_b32 s0, v255, 42
	v_readlane_b32 s1, v255, 43
	v_max3_f32 v32, v32, v56, v53
	v_cndmask_b32_e64 v37, v18, v200, s[70:71]
	v_cndmask_b32_e64 v54, v38, v200, s[0:1]
	v_cmp_gt_i32_e64 s[0:1], v100, v96
	s_or_b64 s[0:1], vcc, s[0:1]
	s_or_b64 vcc, s[0:1], s[42:43]
	v_cndmask_b32_e32 v0, v0, v200, vcc
	v_cmp_le_i32_e32 vcc, v119, v96
	v_cmp_gt_i32_e64 s[0:1], v119, v94
	s_or_b64 s[0:1], vcc, s[0:1]
	s_or_b64 vcc, s[0:1], s[4:5]
	v_cndmask_b32_e32 v1, v1, v200, vcc
	v_cmp_le_i32_e32 vcc, v120, v96
	v_cmp_gt_i32_e64 s[0:1], v120, v94
	s_or_b64 s[0:1], vcc, s[0:1]
	s_or_b64 vcc, s[0:1], s[48:49]
	v_cndmask_b32_e32 v2, v2, v200, vcc
	v_cmp_le_i32_e32 vcc, v121, v96
	v_cmp_gt_i32_e64 s[0:1], v121, v94
	s_or_b64 s[0:1], vcc, s[0:1]
	s_or_b64 vcc, s[0:1], s[8:9]
	v_cndmask_b32_e32 v3, v3, v200, vcc
	v_cmp_le_i32_e32 vcc, v122, v96
	v_cmp_gt_i32_e64 s[0:1], v122, v94
	s_or_b64 s[0:1], vcc, s[0:1]
	s_or_b64 vcc, s[0:1], s[10:11]
	v_cndmask_b32_e32 v4, v4, v200, vcc
	v_cmp_le_i32_e32 vcc, v123, v96
	v_cmp_gt_i32_e64 s[0:1], v123, v94
	s_or_b64 s[0:1], vcc, s[0:1]
	s_or_b64 vcc, s[0:1], s[12:13]
	v_cndmask_b32_e32 v5, v5, v200, vcc
	v_cmp_le_i32_e32 vcc, v124, v96
	v_cmp_gt_i32_e64 s[0:1], v124, v94
	s_or_b64 s[0:1], vcc, s[0:1]
	s_or_b64 vcc, s[0:1], s[14:15]
	v_cndmask_b32_e32 v6, v6, v200, vcc
	v_cmp_le_i32_e32 vcc, v125, v96
	v_cmp_gt_i32_e64 s[0:1], v125, v94
	s_or_b64 s[0:1], vcc, s[0:1]
	s_or_b64 vcc, s[0:1], s[16:17]
	v_cndmask_b32_e32 v7, v7, v200, vcc
	v_cmp_le_i32_e32 vcc, v126, v96
	v_cmp_gt_i32_e64 s[0:1], v126, v94
	s_or_b64 s[0:1], vcc, s[0:1]
	s_or_b64 vcc, s[0:1], s[18:19]
	v_cndmask_b32_e32 v8, v8, v200, vcc
	v_cmp_le_i32_e32 vcc, v127, v96
	v_cmp_gt_i32_e64 s[0:1], v127, v94
	s_or_b64 s[0:1], vcc, s[0:1]
	s_or_b64 vcc, s[0:1], s[20:21]
	v_max3_f32 v32, v32, v54, v52
	v_cndmask_b32_e32 v9, v9, v200, vcc
	v_cmp_le_i32_e32 vcc, v128, v96
	v_cmp_gt_i32_e64 s[0:1], v128, v94
	v_max3_f32 v32, v32, v51, v50
	s_or_b64 s[0:1], vcc, s[0:1]
	v_max3_f32 v32, v32, v49, v48
	s_or_b64 vcc, s[0:1], s[22:23]
	v_max3_f32 v32, v32, v43, v42
	v_cndmask_b32_e32 v10, v10, v200, vcc
	v_cmp_le_i32_e32 vcc, v129, v96
	v_cmp_gt_i32_e64 s[0:1], v129, v94
	v_max3_f32 v32, v32, v41, v40
	v_cndmask_b32_e64 v38, v17, v200, s[68:69]
	s_or_b64 s[0:1], vcc, s[0:1]
	v_max3_f32 v16, v32, v39, v38
	s_or_b64 vcc, s[0:1], s[24:25]
	v_max3_f32 v16, v16, v37, v36
	v_cndmask_b32_e32 v11, v11, v200, vcc
	v_cmp_le_i32_e32 vcc, v130, v96
	v_cmp_gt_i32_e64 s[0:1], v130, v94
	v_max3_f32 v16, v16, v35, v34
	v_cndmask_b32_e64 v32, v23, v200, s[80:81]
	s_or_b64 s[0:1], vcc, s[0:1]
	v_max3_f32 v16, v16, v33, v32
	v_cndmask_b32_e64 v23, v24, v200, s[82:83]
	v_cndmask_b32_e64 v22, v25, v200, s[84:85]
	s_or_b64 vcc, s[0:1], s[26:27]
	v_max3_f32 v16, v16, v23, v22
	v_cndmask_b32_e64 v21, v26, v200, s[86:87]
	v_cndmask_b32_e64 v20, v27, v200, s[88:89]
	v_cndmask_b32_e32 v12, v12, v200, vcc
	v_cmp_le_i32_e32 vcc, v131, v96
	v_cmp_gt_i32_e64 s[0:1], v131, v94
	v_max3_f32 v16, v16, v21, v20
	v_cndmask_b32_e64 v19, v28, v200, s[90:91]
	v_cndmask_b32_e64 v18, v29, v200, s[92:93]
	s_or_b64 s[0:1], vcc, s[0:1]
	v_max3_f32 v24, v16, v19, v18
	v_cndmask_b32_e64 v17, v30, v200, s[94:95]
	v_cndmask_b32_e64 v16, v31, v200, s[96:97]
	s_or_b64 vcc, s[0:1], s[28:29]
	v_max3_f32 v24, v24, v17, v16
	v_cndmask_b32_e32 v13, v13, v200, vcc
	v_cmp_le_i32_e32 vcc, v132, v96
	v_cmp_gt_i32_e64 s[0:1], v132, v94
	v_max3_f32 v24, v24, v0, v1
	s_or_b64 s[0:1], vcc, s[0:1]
	v_max3_f32 v24, v24, v2, v3
	s_or_b64 vcc, s[0:1], s[30:31]
	v_max3_f32 v24, v24, v4, v5
	v_cndmask_b32_e32 v14, v14, v200, vcc
	v_cmp_le_i32_e32 vcc, v133, v96
	v_cmp_gt_i32_e64 s[0:1], v133, v94
	v_max3_f32 v24, v24, v6, v7
	s_or_b64 s[0:1], vcc, s[0:1]
	v_and_b32_e32 v26, 64, v198
	v_max3_f32 v24, v24, v8, v9
	s_or_b64 vcc, s[0:1], s[34:35]
	v_xor_b32_e32 v25, 32, v198
	v_add_u32_e32 v26, 64, v26
	v_max3_f32 v24, v24, v10, v11
	v_cndmask_b32_e32 v15, v15, v200, vcc
	v_cmp_lt_i32_e32 vcc, v25, v26
	v_max3_f32 v24, v24, v12, v13
	v_max3_f32 v24, v24, v14, v15
	v_cndmask_b32_e32 v25, v198, v25, vcc
	v_lshlrev_b32_e32 v25, 2, v25
	ds_bpermute_b32 v26, v25, v24
	s_lshr_b32 s1, s39, 2
	s_mulk_i32 s1, 0x4080
	s_add_i32 s2, s1, 0x20400
	s_add_i32 s0, s44, s33
	s_waitcnt lgkmcnt(0)
	v_max_f32_e32 v26, v26, v26
	v_max_f32_e32 v24, v24, v26
	v_sub_f32_e32 v26, v64, v24
	v_mul_f32_e32 v26, 0x3fb8aa3b, v26
	v_sub_f32_e32 v28, v65, v24
	v_exp_f32_e32 v26, v26
	v_mul_f32_e32 v28, 0x3fb8aa3b, v28
	v_sub_f32_e32 v29, v66, v24
	v_exp_f32_e32 v28, v28
	v_mul_f32_e32 v29, 0x3fb8aa3b, v29
	v_sub_f32_e32 v30, v67, v24
	v_exp_f32_e32 v29, v29
	v_mul_f32_e32 v30, 0x3fb8aa3b, v30
	v_sub_f32_e32 v31, v68, v24
	v_exp_f32_e32 v30, v30
	v_mul_f32_e32 v31, 0x3fb8aa3b, v31
	v_sub_f32_e32 v44, v69, v24
	v_add_f32_e32 v27, 0, v26
	v_exp_f32_e32 v31, v31
	v_mul_f32_e32 v44, 0x3fb8aa3b, v44
	v_sub_f32_e32 v45, v70, v24
	v_add_f32_e32 v27, v28, v27
	v_exp_f32_e32 v44, v44
	v_mul_f32_e32 v45, 0x3fb8aa3b, v45
	v_sub_f32_e32 v46, v71, v24
	v_add_f32_e32 v27, v29, v27
	v_exp_f32_e32 v45, v45
	v_mul_f32_e32 v46, 0x3fb8aa3b, v46
	v_sub_f32_e32 v47, v72, v24
	v_add_f32_e32 v27, v30, v27
	v_exp_f32_e32 v46, v46
	v_mul_f32_e32 v47, 0x3fb8aa3b, v47
	v_sub_f32_e32 v63, v73, v24
	v_add_f32_e32 v27, v31, v27
	v_exp_f32_e32 v47, v47
	v_mul_f32_e32 v63, 0x3fb8aa3b, v63
	v_sub_f32_e32 v64, v74, v24
	v_add_f32_e32 v27, v44, v27
	v_exp_f32_e32 v63, v63
	v_mul_f32_e32 v64, 0x3fb8aa3b, v64
	v_sub_f32_e32 v65, v75, v24
	v_add_f32_e32 v27, v45, v27
	v_exp_f32_e32 v64, v64
	v_mul_f32_e32 v65, 0x3fb8aa3b, v65
	v_sub_f32_e32 v66, v76, v24
	v_add_f32_e32 v27, v46, v27
	v_exp_f32_e32 v65, v65
	v_mul_f32_e32 v66, 0x3fb8aa3b, v66
	v_sub_f32_e32 v67, v77, v24
	v_add_f32_e32 v27, v47, v27
	v_exp_f32_e32 v66, v66
	v_mul_f32_e32 v67, 0x3fb8aa3b, v67
	v_sub_f32_e32 v68, v85, v24
	v_add_f32_e32 v27, v63, v27
	v_exp_f32_e32 v67, v67
	v_mul_f32_e32 v68, 0x3fb8aa3b, v68
	v_sub_f32_e32 v69, v92, v24
	v_add_f32_e32 v27, v64, v27
	v_exp_f32_e32 v68, v68
	v_mul_f32_e32 v69, 0x3fb8aa3b, v69
	v_sub_f32_e32 v70, v93, v24
	v_add_f32_e32 v27, v65, v27
	v_exp_f32_e32 v69, v69
	v_mul_f32_e32 v70, 0x3fb8aa3b, v70
	v_sub_f32_e32 v71, v90, v24
	v_add_f32_e32 v27, v66, v27
	v_exp_f32_e32 v70, v70
	v_mul_f32_e32 v71, 0x3fb8aa3b, v71
	v_sub_f32_e32 v72, v91, v24
	v_add_f32_e32 v27, v67, v27
	v_exp_f32_e32 v71, v71
	v_mul_f32_e32 v72, 0x3fb8aa3b, v72
	v_sub_f32_e32 v73, v88, v24
	v_add_f32_e32 v27, v68, v27
	v_exp_f32_e32 v72, v72
	v_mul_f32_e32 v73, 0x3fb8aa3b, v73
	v_sub_f32_e32 v74, v89, v24
	v_add_f32_e32 v27, v69, v27
	v_exp_f32_e32 v73, v73
	v_mul_f32_e32 v74, 0x3fb8aa3b, v74
	v_sub_f32_e32 v75, v86, v24
	v_add_f32_e32 v27, v70, v27
	v_exp_f32_e32 v74, v74
	v_mul_f32_e32 v75, 0x3fb8aa3b, v75
	v_sub_f32_e32 v76, v87, v24
	v_add_f32_e32 v27, v71, v27
	v_exp_f32_e32 v75, v75
	v_mul_f32_e32 v76, 0x3fb8aa3b, v76
	v_sub_f32_e32 v77, v83, v24
	v_add_f32_e32 v27, v72, v27
	v_exp_f32_e32 v76, v76
	v_mul_f32_e32 v77, 0x3fb8aa3b, v77
	v_sub_f32_e32 v83, v84, v24
	v_add_f32_e32 v27, v73, v27
	v_exp_f32_e32 v77, v77
	v_mul_f32_e32 v83, 0x3fb8aa3b, v83
	v_sub_f32_e32 v81, v81, v24
	v_add_f32_e32 v27, v74, v27
	v_exp_f32_e32 v83, v83
	v_mul_f32_e32 v81, 0x3fb8aa3b, v81
	v_sub_f32_e32 v82, v82, v24
	v_add_f32_e32 v27, v75, v27
	v_exp_f32_e32 v81, v81
	v_mul_f32_e32 v82, 0x3fb8aa3b, v82
	v_sub_f32_e32 v78, v78, v24
	v_add_f32_e32 v27, v76, v27
	v_exp_f32_e32 v82, v82
	v_mul_f32_e32 v78, 0x3fb8aa3b, v78
	v_sub_f32_e32 v79, v79, v24
	v_add_f32_e32 v27, v77, v27
	v_exp_f32_e32 v78, v78
	v_mul_f32_e32 v79, 0x3fb8aa3b, v79
	v_sub_f32_e32 v61, v61, v24
	v_add_f32_e32 v27, v83, v27
	v_exp_f32_e32 v79, v79
	v_mul_f32_e32 v61, 0x3fb8aa3b, v61
	v_sub_f32_e32 v62, v62, v24
	v_add_f32_e32 v27, v81, v27
	v_exp_f32_e32 v61, v61
	v_mul_f32_e32 v62, 0x3fb8aa3b, v62
	v_sub_f32_e32 v59, v59, v24
	v_add_f32_e32 v27, v82, v27
	v_exp_f32_e32 v62, v62
	v_mul_f32_e32 v59, 0x3fb8aa3b, v59
	v_sub_f32_e32 v60, v60, v24
	v_add_f32_e32 v27, v78, v27
	v_exp_f32_e32 v59, v59
	v_mul_f32_e32 v60, 0x3fb8aa3b, v60
	v_sub_f32_e32 v57, v57, v24
	v_add_f32_e32 v27, v79, v27
	v_exp_f32_e32 v60, v60
	v_mul_f32_e32 v57, 0x3fb8aa3b, v57
	v_sub_f32_e32 v58, v58, v24
	v_add_f32_e32 v27, v61, v27
	v_exp_f32_e32 v57, v57
	v_mul_f32_e32 v58, 0x3fb8aa3b, v58
	v_sub_f32_e32 v55, v55, v24
	v_add_f32_e32 v27, v62, v27
	v_exp_f32_e32 v58, v58
	v_mul_f32_e32 v55, 0x3fb8aa3b, v55
	v_sub_f32_e32 v56, v56, v24
	v_add_f32_e32 v27, v59, v27
	v_exp_f32_e32 v55, v55
	v_mul_f32_e32 v56, 0x3fb8aa3b, v56
	v_sub_f32_e32 v53, v53, v24
	v_add_f32_e32 v27, v60, v27
	v_exp_f32_e32 v56, v56
	v_mul_f32_e32 v53, 0x3fb8aa3b, v53
	v_sub_f32_e32 v54, v54, v24
	v_add_f32_e32 v27, v57, v27
	v_exp_f32_e32 v53, v53
	v_mul_f32_e32 v54, 0x3fb8aa3b, v54
	v_sub_f32_e32 v52, v52, v24
	v_add_f32_e32 v27, v58, v27
	v_exp_f32_e32 v54, v54
	v_mul_f32_e32 v52, 0x3fb8aa3b, v52
	v_sub_f32_e32 v51, v51, v24
	v_add_f32_e32 v27, v55, v27
	v_exp_f32_e32 v52, v52
	v_mul_f32_e32 v51, 0x3fb8aa3b, v51
	v_sub_f32_e32 v50, v50, v24
	v_add_f32_e32 v27, v56, v27
	v_exp_f32_e32 v51, v51
	v_mul_f32_e32 v50, 0x3fb8aa3b, v50
	v_sub_f32_e32 v49, v49, v24
	v_add_f32_e32 v27, v53, v27
	v_exp_f32_e32 v50, v50
	v_mul_f32_e32 v49, 0x3fb8aa3b, v49
	v_sub_f32_e32 v48, v48, v24
	v_add_f32_e32 v27, v54, v27
	v_exp_f32_e32 v49, v49
	v_mul_f32_e32 v48, 0x3fb8aa3b, v48
	v_sub_f32_e32 v43, v43, v24
	v_add_f32_e32 v27, v52, v27
	v_exp_f32_e32 v48, v48
	v_mul_f32_e32 v43, 0x3fb8aa3b, v43
	v_sub_f32_e32 v42, v42, v24
	v_add_f32_e32 v27, v51, v27
	v_exp_f32_e32 v84, v43
	v_mul_f32_e32 v42, 0x3fb8aa3b, v42
	v_sub_f32_e32 v41, v41, v24
	v_add_f32_e32 v27, v50, v27
	v_exp_f32_e32 v85, v42
	v_mul_f32_e32 v41, 0x3fb8aa3b, v41
	v_sub_f32_e32 v40, v40, v24
	v_add_f32_e32 v27, v49, v27
	v_exp_f32_e32 v86, v41
	v_mul_f32_e32 v40, 0x3fb8aa3b, v40
	v_sub_f32_e32 v39, v39, v24
	v_add_f32_e32 v27, v48, v27
	v_exp_f32_e32 v87, v40
	v_mul_f32_e32 v39, 0x3fb8aa3b, v39
	v_sub_f32_e32 v38, v38, v24
	v_add_f32_e32 v27, v84, v27
	v_exp_f32_e32 v88, v39
	v_mul_f32_e32 v38, 0x3fb8aa3b, v38
	v_sub_f32_e32 v37, v37, v24
	v_add_f32_e32 v27, v85, v27
	v_exp_f32_e32 v89, v38
	v_mul_f32_e32 v37, 0x3fb8aa3b, v37
	v_sub_f32_e32 v36, v36, v24
	v_sub_f32_e32 v1, v1, v24
	v_add_f32_e32 v27, v86, v27
	v_exp_f32_e32 v90, v37
	v_mul_f32_e32 v36, 0x3fb8aa3b, v36
	v_sub_f32_e32 v35, v35, v24
	v_mul_f32_e32 v1, 0x3fb8aa3b, v1
	v_add_f32_e32 v27, v87, v27
	v_exp_f32_e32 v91, v36
	v_mul_f32_e32 v35, 0x3fb8aa3b, v35
	v_sub_f32_e32 v34, v34, v24
	v_exp_f32_e32 v142, v1
	v_sub_f32_e32 v1, v2, v24
	v_add_f32_e32 v27, v88, v27
	v_exp_f32_e32 v35, v35
	v_mul_f32_e32 v34, 0x3fb8aa3b, v34
	v_sub_f32_e32 v33, v33, v24
	v_mul_f32_e32 v1, 0x3fb8aa3b, v1
	v_add_f32_e32 v27, v89, v27
	v_exp_f32_e32 v92, v34
	v_mul_f32_e32 v33, 0x3fb8aa3b, v33
	v_sub_f32_e32 v32, v32, v24
	v_exp_f32_e32 v143, v1
	v_sub_f32_e32 v1, v3, v24
	v_add_f32_e32 v27, v90, v27
	v_exp_f32_e32 v33, v33
	v_mul_f32_e32 v32, 0x3fb8aa3b, v32
	v_sub_f32_e32 v23, v23, v24
	v_mul_f32_e32 v1, 0x3fb8aa3b, v1
	v_add_f32_e32 v27, v91, v27
	v_exp_f32_e32 v32, v32
	v_mul_f32_e32 v23, 0x3fb8aa3b, v23
	v_sub_f32_e32 v22, v22, v24
	v_exp_f32_e32 v144, v1
	v_sub_f32_e32 v1, v4, v24
	v_add_f32_e32 v27, v35, v27
	v_exp_f32_e32 v93, v23
	v_mul_f32_e32 v22, 0x3fb8aa3b, v22
	v_sub_f32_e32 v21, v21, v24
	v_mul_f32_e32 v1, 0x3fb8aa3b, v1
	v_add_f32_e32 v27, v92, v27
	v_exp_f32_e32 v94, v22
	v_mul_f32_e32 v21, 0x3fb8aa3b, v21
	v_sub_f32_e32 v20, v20, v24
	v_exp_f32_e32 v145, v1
	v_sub_f32_e32 v1, v5, v24
	v_add_f32_e32 v27, v33, v27
	v_exp_f32_e32 v95, v21
	v_mul_f32_e32 v20, 0x3fb8aa3b, v20
	v_sub_f32_e32 v19, v19, v24
	v_mul_f32_e32 v1, 0x3fb8aa3b, v1
	v_add_f32_e32 v27, v32, v27
	v_exp_f32_e32 v96, v20
	v_mul_f32_e32 v19, 0x3fb8aa3b, v19
	v_sub_f32_e32 v18, v18, v24
	v_exp_f32_e32 v146, v1
	v_sub_f32_e32 v1, v6, v24
	v_add_f32_e32 v23, v93, v27
	v_exp_f32_e32 v137, v19
	v_mul_f32_e32 v18, 0x3fb8aa3b, v18
	v_sub_f32_e32 v17, v17, v24
	v_mul_f32_e32 v1, 0x3fb8aa3b, v1
	v_add_f32_e32 v22, v94, v23
	v_exp_f32_e32 v138, v18
	v_mul_f32_e32 v17, 0x3fb8aa3b, v17
	v_sub_f32_e32 v16, v16, v24
	v_exp_f32_e32 v147, v1
	v_sub_f32_e32 v1, v7, v24
	v_add_f32_e32 v21, v95, v22
	v_exp_f32_e32 v139, v17
	v_mul_f32_e32 v16, 0x3fb8aa3b, v16
	v_sub_f32_e32 v0, v0, v24
	v_mul_f32_e32 v1, 0x3fb8aa3b, v1
	v_add_f32_e32 v20, v96, v21
	v_exp_f32_e32 v140, v16
	v_mul_f32_e32 v0, 0x3fb8aa3b, v0
	v_exp_f32_e32 v148, v1
	v_sub_f32_e32 v1, v8, v24
	v_add_f32_e32 v19, v137, v20
	v_exp_f32_e32 v141, v0
	v_mul_f32_e32 v1, 0x3fb8aa3b, v1
	v_add_f32_e32 v18, v138, v19
	v_exp_f32_e32 v149, v1
	v_sub_f32_e32 v1, v9, v24
	v_add_f32_e32 v17, v139, v18
	v_mul_f32_e32 v1, 0x3fb8aa3b, v1
	v_add_f32_e32 v16, v140, v17
	v_exp_f32_e32 v150, v1
	v_sub_f32_e32 v1, v10, v24
	v_add_f32_e32 v0, v141, v16
	v_mul_f32_e32 v1, 0x3fb8aa3b, v1
	v_add_f32_e32 v0, v142, v0
	v_exp_f32_e32 v151, v1
	v_sub_f32_e32 v1, v11, v24
	v_add_f32_e32 v0, v143, v0
	v_mul_f32_e32 v1, 0x3fb8aa3b, v1
	v_add_f32_e32 v0, v144, v0
	v_exp_f32_e32 v152, v1
	v_sub_f32_e32 v1, v12, v24
	v_add_f32_e32 v0, v145, v0
	v_mul_f32_e32 v1, 0x3fb8aa3b, v1
	v_add_f32_e32 v0, v146, v0
	v_exp_f32_e32 v153, v1
	v_sub_f32_e32 v1, v13, v24
	v_add_f32_e32 v0, v147, v0
	v_mul_f32_e32 v1, 0x3fb8aa3b, v1
	v_add_f32_e32 v0, v148, v0
	v_exp_f32_e32 v154, v1
	v_sub_f32_e32 v1, v14, v24
	v_add_f32_e32 v0, v149, v0
	v_mul_f32_e32 v1, 0x3fb8aa3b, v1
	v_add_f32_e32 v0, v150, v0
	v_exp_f32_e32 v155, v1
	v_sub_f32_e32 v1, v15, v24
	v_add_f32_e32 v0, v151, v0
	v_mul_f32_e32 v1, 0x3fb8aa3b, v1
	v_add_f32_e32 v0, v152, v0
	v_exp_f32_e32 v156, v1
	v_add_f32_e32 v0, v153, v0
	v_add_f32_e32 v0, v154, v0
	v_add_f32_e32 v0, v155, v0
	v_add_f32_e32 v0, v156, v0
	ds_bpermute_b32 v1, v25, v0
	v_cvt_pk_bf16_f32 v2, v31, v44
	v_add_u32_e32 v44, 0x9000, v136
	ds_read2_b64 v[4:7], v44 offset1:2
	ds_read2_b64 v[36:39], v44 offset0:4 offset1:6
	v_cvt_pk_bf16_f32 v3, v45, v46
	s_waitcnt lgkmcnt(2)
	v_add_f32_e32 v0, v0, v1
	v_sub_f32_e32 v1, v80, v24
	v_mul_f32_e32 v1, 0x3fb8aa3b, v1
	v_exp_f32_e32 v1, v1
	v_add_u32_e32 v45, 0xd000, v136
	v_cvt_pk_bf16_f32 v40, v47, v63
	v_cvt_pk_bf16_f32 v41, v64, v65
	v_add_f32_e32 v34, v1, v0
	v_cvt_pk_bf16_f32 v0, v26, v28
	v_cvt_pk_bf16_f32 v1, v29, v30
	v_cvt_pk_bf16_f32 v42, v66, v67
	v_cvt_pk_bf16_f32 v43, v68, v69
	s_waitcnt lgkmcnt(1)
	v_mfma_f32_32x32x16_bf16 v[16:31], v[4:7], v[0:3], 0
	ds_read2_b64 v[4:7], v45 offset0:96 offset1:98
	s_and_b32 s0, s0, 0xc0
	s_mov_b64 vcc, s[46:47]
	v_readlane_b32 s1, v254, 36
	s_add_i32 s33, s33, 64
	v_mov_b32_e32 v203, 0
	v_lshl_add_u64 v[192:193], s[2:3], 0, v[98:99]
	v_lshlrev_b64 v[192:193], 9, v[192:193]
	v_lshl_add_u64 v[192:193], vcc, 0, v[192:193]
	s_lshl_b32 s2, s0, 1
	v_lshl_add_u64 v[192:193], v[192:193], 0, s[2:3]
	s_and_b32 s0, s38, 4
	s_or_b32 s0, s0, s1
	s_lshr_b32 s0, s0, 2
	v_lshlrev_b32_e32 v202, 1, v100
	v_lshl_add_u64 v[192:193], v[192:193], 0, v[202:203]
	s_mul_i32 s2, s0, 0x4080
	v_lshl_add_u64 v[194:195], s[2:3], 0, v[98:99]
	s_and_b32 s0, s33, 0xc0
	v_or_b32_e32 v196, s0, v134
	v_lshlrev_b64 v[194:195], 9, v[194:195]
	v_lshl_add_u64 v[194:195], vcc, 0, v[194:195]
	v_lshlrev_b32_e32 v202, 1, v196
	v_lshl_add_u64 v[194:195], v[194:195], 0, v[202:203]
	v_lshl_add_u64 v[224:225], v[192:193], 0, v[206:207]
	global_load_dwordx4 v[160:163], v[224:225], off
	global_load_dwordx4 v[164:167], v[224:225], off offset:32
	global_load_dwordx4 v[168:171], v[224:225], off offset:64
	global_load_dwordx4 v[172:175], v[224:225], off offset:96
	global_load_dwordx4 v[176:179], v[194:195], off
	global_load_dwordx4 v[180:183], v[194:195], off offset:32
	global_load_dwordx4 v[184:187], v[194:195], off offset:64
	global_load_dwordx4 v[188:191], v[194:195], off offset:96
	v_rcp_f32_e32 v34, v34
	s_waitcnt lgkmcnt(1)
	v_mfma_f32_32x32x16_bf16 v[16:31], v[36:39], v[40:43], v[16:31]
	ds_read2_b64 v[36:39], v45 offset0:100 offset1:102
	s_waitcnt lgkmcnt(1)
	v_mfma_f32_32x32x16_bf16 v[0:15], v[4:7], v[0:3], 0
	s_waitcnt lgkmcnt(0)
	v_mfma_f32_32x32x16_bf16 v[0:15], v[36:39], v[40:43], v[0:15]
	ds_read2_b64 v[40:43], v44 offset0:8 offset1:10
	v_cvt_pk_bf16_f32 v36, v70, v71
	v_cvt_pk_bf16_f32 v37, v72, v73
	v_cvt_pk_bf16_f32 v38, v74, v75
	v_cvt_pk_bf16_f32 v39, v76, v77
	s_waitcnt lgkmcnt(0)
	s_nop 0
	v_mfma_f32_32x32x16_bf16 v[16:31], v[40:43], v[36:39], v[16:31]
	ds_read2_b64 v[40:43], v45 offset0:104 offset1:106
	s_waitcnt lgkmcnt(0)
	v_mfma_f32_32x32x16_bf16 v[0:15], v[40:43], v[36:39], v[0:15]
	ds_read2_b64 v[40:43], v44 offset0:12 offset1:14
	v_cvt_pk_bf16_f32 v36, v83, v81
	v_cvt_pk_bf16_f32 v37, v82, v78
	v_cvt_pk_bf16_f32 v38, v79, v61
	v_cvt_pk_bf16_f32 v39, v62, v59
	s_waitcnt lgkmcnt(0)
	s_nop 0
	v_mfma_f32_32x32x16_bf16 v[16:31], v[40:43], v[36:39], v[16:31]
	ds_read2_b64 v[40:43], v45 offset0:108 offset1:110
	s_waitcnt lgkmcnt(0)
	v_mfma_f32_32x32x16_bf16 v[0:15], v[40:43], v[36:39], v[0:15]
	ds_read2_b64 v[40:43], v44 offset0:16 offset1:18
	v_cvt_pk_bf16_f32 v36, v60, v57
	v_cvt_pk_bf16_f32 v37, v58, v55
	v_cvt_pk_bf16_f32 v38, v56, v53
	v_cvt_pk_bf16_f32 v39, v54, v52
	s_waitcnt lgkmcnt(0)
	s_nop 0
	v_mfma_f32_32x32x16_bf16 v[16:31], v[40:43], v[36:39], v[16:31]
	ds_read2_b64 v[40:43], v45 offset0:112 offset1:114
	s_waitcnt lgkmcnt(0)
	v_mfma_f32_32x32x16_bf16 v[0:15], v[40:43], v[36:39], v[0:15]
	ds_read2_b64 v[40:43], v44 offset0:20 offset1:22
	v_cvt_pk_bf16_f32 v36, v51, v50
	v_cvt_pk_bf16_f32 v37, v49, v48
	v_cvt_pk_bf16_f32 v38, v84, v85
	v_cvt_pk_bf16_f32 v39, v86, v87
	s_waitcnt lgkmcnt(0)
	s_nop 0
	v_mfma_f32_32x32x16_bf16 v[16:31], v[40:43], v[36:39], v[16:31]
	ds_read2_b64 v[40:43], v45 offset0:116 offset1:118
	s_waitcnt lgkmcnt(0)
	v_mfma_f32_32x32x16_bf16 v[0:15], v[40:43], v[36:39], v[0:15]
	ds_read2_b64 v[40:43], v44 offset0:24 offset1:26
	v_cvt_pk_bf16_f32 v36, v88, v89
	v_cvt_pk_bf16_f32 v37, v90, v91
	v_cvt_pk_bf16_f32 v38, v35, v92
	v_cvt_pk_bf16_f32 v39, v33, v32
	s_waitcnt lgkmcnt(0)
	s_nop 0
	v_mfma_f32_32x32x16_bf16 v[16:31], v[40:43], v[36:39], v[16:31]
	ds_read2_b64 v[40:43], v45 offset0:120 offset1:122
	s_waitcnt lgkmcnt(0)
	v_mfma_f32_32x32x16_bf16 v[0:15], v[40:43], v[36:39], v[0:15]
	ds_read2_b64 v[40:43], v44 offset0:28 offset1:30
	v_cvt_pk_bf16_f32 v36, v93, v94
	v_cvt_pk_bf16_f32 v37, v95, v96
	v_cvt_pk_bf16_f32 v38, v137, v138
	v_cvt_pk_bf16_f32 v39, v139, v140
	s_waitcnt lgkmcnt(0)
	s_nop 0
	v_mfma_f32_32x32x16_bf16 v[16:31], v[40:43], v[36:39], v[16:31]
	ds_read2_b64 v[40:43], v45 offset0:124 offset1:126
	s_waitcnt lgkmcnt(0)
	v_mfma_f32_32x32x16_bf16 v[0:15], v[40:43], v[36:39], v[0:15]
	ds_read2_b64 v[40:43], v44 offset0:32 offset1:34
	v_cvt_pk_bf16_f32 v36, v141, v142
	v_cvt_pk_bf16_f32 v37, v143, v144
	v_cvt_pk_bf16_f32 v38, v145, v146
	v_cvt_pk_bf16_f32 v39, v147, v148
	s_waitcnt lgkmcnt(0)
	s_nop 0
	v_mfma_f32_32x32x16_bf16 v[16:31], v[40:43], v[36:39], v[16:31]
	ds_read2_b64 v[40:43], v45 offset0:128 offset1:130
	s_add_u32 s36, s36, 4
	s_addc_u32 s37, s37, 0
	s_mov_b64 s[0:1], 0x80
	s_cmp_eq_u32 s38, 8
	s_waitcnt lgkmcnt(0)
	v_mfma_f32_32x32x16_bf16 v[0:15], v[40:43], v[36:39], v[0:15]
	ds_read2_b64 v[40:43], v44 offset0:36 offset1:38
	v_cvt_pk_bf16_f32 v36, v149, v150
	v_cvt_pk_bf16_f32 v37, v151, v152
	v_cvt_pk_bf16_f32 v38, v153, v154
	v_cvt_pk_bf16_f32 v39, v155, v156
	s_waitcnt lgkmcnt(0)
	s_nop 0
	v_mfma_f32_32x32x16_bf16 v[16:31], v[40:43], v[36:39], v[16:31]
	ds_read2_b64 v[40:43], v45 offset0:132 offset1:134
	s_waitcnt lgkmcnt(0)
	v_mfma_f32_32x32x16_bf16 v[0:15], v[40:43], v[36:39], v[0:15]
	s_nop 0
	s_nop 0
	s_nop 6
	v_pk_mul_f32 v[16:17], v[16:17], v[34:35] op_sel_hi:[1,0]
	v_pk_mul_f32 v[18:19], v[18:19], v[34:35] op_sel_hi:[1,0]
	s_nop 0
	v_pk_mul_f32 v[0:1], v[0:1], v[34:35] op_sel_hi:[1,0]
	v_pk_mul_f32 v[2:3], v[2:3], v[34:35] op_sel_hi:[1,0]
	v_lshl_add_u64 v[204:205], v[102:103], 0, v[206:207]
	s_waitcnt vmcnt(7)
	s_nop 1
	v_permlane32_swap_b32_e32 v160, v162
	v_permlane32_swap_b32_e32 v161, v163
	v_lshlrev_b32_e32 v50, 16, v160
	v_and_b32_e32 v51, 0xffff0000, v160
	v_lshlrev_b32_e32 v48, 16, v161
	v_and_b32_e32 v49, 0xffff0000, v161
	v_pk_mul_f32 v[16:17], v[16:17], v[50:51]
	v_pk_mul_f32 v[18:19], v[18:19], v[48:49]
	v_cvt_pk_bf16_f32 v208, v16, v17
	v_cvt_pk_bf16_f32 v209, v18, v19
	v_pk_mul_f32 v[16:17], v[20:21], v[34:35] op_sel_hi:[1,0]
	s_waitcnt vmcnt(7)
	v_lshlrev_b32_e32 v18, 16, v162
	v_and_b32_e32 v19, 0xffff0000, v162
	v_pk_mul_f32 v[16:17], v[16:17], v[18:19]
	v_pk_mul_f32 v[18:19], v[22:23], v[34:35] op_sel_hi:[1,0]
	v_lshlrev_b32_e32 v20, 16, v163
	v_and_b32_e32 v21, 0xffff0000, v163
	v_pk_mul_f32 v[18:19], v[18:19], v[20:21]
	v_cvt_pk_bf16_f32 v210, v16, v17
	v_cvt_pk_bf16_f32 v211, v18, v19
	s_nop 1
	v_permlane32_swap_b32_e32 v208, v210
	v_permlane32_swap_b32_e32 v209, v211
	global_store_dwordx4 v[204:205], v[208:211], off offset:-64
	v_pk_mul_f32 v[16:17], v[24:25], v[34:35] op_sel_hi:[1,0]
	s_waitcnt vmcnt(7)
	s_nop 1
	v_permlane32_swap_b32_e32 v164, v166
	v_permlane32_swap_b32_e32 v165, v167
	v_lshlrev_b32_e32 v18, 16, v164
	v_and_b32_e32 v19, 0xffff0000, v164
	v_pk_mul_f32 v[16:17], v[16:17], v[18:19]
	v_pk_mul_f32 v[18:19], v[26:27], v[34:35] op_sel_hi:[1,0]
	v_lshlrev_b32_e32 v20, 16, v165
	v_and_b32_e32 v21, 0xffff0000, v165
	v_pk_mul_f32 v[18:19], v[18:19], v[20:21]
	v_cvt_pk_bf16_f32 v212, v16, v17
	v_cvt_pk_bf16_f32 v213, v18, v19
	v_pk_mul_f32 v[16:17], v[28:29], v[34:35] op_sel_hi:[1,0]
	s_waitcnt vmcnt(7)
	v_lshlrev_b32_e32 v18, 16, v166
	v_and_b32_e32 v19, 0xffff0000, v166
	v_pk_mul_f32 v[16:17], v[16:17], v[18:19]
	v_pk_mul_f32 v[18:19], v[30:31], v[34:35] op_sel_hi:[1,0]
	v_lshlrev_b32_e32 v20, 16, v167
	v_and_b32_e32 v21, 0xffff0000, v167
	v_pk_mul_f32 v[18:19], v[18:19], v[20:21]
	v_cvt_pk_bf16_f32 v214, v16, v17
	v_cvt_pk_bf16_f32 v215, v18, v19
	s_nop 1
	v_permlane32_swap_b32_e32 v212, v214
	v_permlane32_swap_b32_e32 v213, v215
	global_store_dwordx4 v[204:205], v[212:215], off offset:-32
	s_waitcnt vmcnt(7)
	s_nop 1
	v_permlane32_swap_b32_e32 v168, v170
	v_permlane32_swap_b32_e32 v169, v171
	v_lshlrev_b32_e32 v16, 16, v168
	v_and_b32_e32 v17, 0xffff0000, v168
	v_pk_mul_f32 v[0:1], v[0:1], v[16:17]
	v_lshlrev_b32_e32 v16, 16, v169
	v_and_b32_e32 v17, 0xffff0000, v169
	v_pk_mul_f32 v[2:3], v[2:3], v[16:17]
	v_cvt_pk_bf16_f32 v216, v0, v1
	v_cvt_pk_bf16_f32 v217, v2, v3
	v_pk_mul_f32 v[0:1], v[4:5], v[34:35] op_sel_hi:[1,0]
	s_waitcnt vmcnt(7)
	v_lshlrev_b32_e32 v2, 16, v170
	v_and_b32_e32 v3, 0xffff0000, v170
	v_pk_mul_f32 v[0:1], v[0:1], v[2:3]
	v_pk_mul_f32 v[2:3], v[6:7], v[34:35] op_sel_hi:[1,0]
	v_lshlrev_b32_e32 v4, 16, v171
	v_and_b32_e32 v5, 0xffff0000, v171
	v_pk_mul_f32 v[2:3], v[2:3], v[4:5]
	v_cvt_pk_bf16_f32 v218, v0, v1
	v_cvt_pk_bf16_f32 v219, v2, v3
	s_nop 1
	v_permlane32_swap_b32_e32 v216, v218
	v_permlane32_swap_b32_e32 v217, v219
	global_store_dwordx4 v[204:205], v[216:219], off
	v_pk_mul_f32 v[0:1], v[8:9], v[34:35] op_sel_hi:[1,0]
	s_waitcnt vmcnt(7)
	s_nop 1
	v_permlane32_swap_b32_e32 v172, v174
	v_permlane32_swap_b32_e32 v173, v175
	v_lshlrev_b32_e32 v2, 16, v172
	v_and_b32_e32 v3, 0xffff0000, v172
	v_pk_mul_f32 v[0:1], v[0:1], v[2:3]
	v_pk_mul_f32 v[2:3], v[10:11], v[34:35] op_sel_hi:[1,0]
	v_lshlrev_b32_e32 v4, 16, v173
	v_and_b32_e32 v5, 0xffff0000, v173
	v_pk_mul_f32 v[2:3], v[2:3], v[4:5]
	v_cvt_pk_bf16_f32 v220, v0, v1
	v_cvt_pk_bf16_f32 v221, v2, v3
	v_pk_mul_f32 v[0:1], v[12:13], v[34:35] op_sel_hi:[1,0]
	s_waitcnt vmcnt(7)
	v_lshlrev_b32_e32 v2, 16, v174
	v_and_b32_e32 v3, 0xffff0000, v174
	v_pk_mul_f32 v[0:1], v[0:1], v[2:3]
	v_pk_mul_f32 v[2:3], v[14:15], v[34:35] op_sel_hi:[1,0]
	v_lshlrev_b32_e32 v4, 16, v175
	v_and_b32_e32 v5, 0xffff0000, v175
	v_pk_mul_f32 v[2:3], v[2:3], v[4:5]
	v_cvt_pk_bf16_f32 v222, v0, v1
	v_cvt_pk_bf16_f32 v223, v2, v3
	s_nop 1
	v_permlane32_swap_b32_e32 v220, v222
	v_permlane32_swap_b32_e32 v221, v223
	global_store_dwordx4 v[204:205], v[220:223], off offset:32
	v_lshl_add_u64 v[102:103], v[102:103], 0, s[0:1]
	s_waitcnt vmcnt(4)
	v_mov_b32_e32 v80, v176
	v_mov_b32_e32 v81, v177
	v_mov_b32_e32 v82, v178
	v_mov_b32_e32 v83, v179
	v_mov_b32_e32 v84, v180
	v_mov_b32_e32 v85, v181
	v_mov_b32_e32 v86, v182
	v_mov_b32_e32 v87, v183
	v_mov_b32_e32 v88, v184
	v_mov_b32_e32 v89, v185
	v_mov_b32_e32 v90, v186
	v_mov_b32_e32 v91, v187
	v_mov_b32_e32 v92, v188
	v_mov_b32_e32 v93, v189
	v_mov_b32_e32 v94, v190
	v_mov_b32_e32 v95, v191
	s_cbranch_scc0 .LBB0_2056
	v_readlane_b32 s91, v254, 17
	v_readlane_b32 s24, v254, 52
	s_mov_b32 s37, s3
	s_movk_i32 s25, 0x90
	s_branch .LBB0_1999
